# MIXC row loops batched 16 rows per round trip (48 loads in flight) instead of one row per round trip
# speedup vs baseline: 1.0235x; 1.0235x over previous
; __device__ __forceinline__ float bf2f(bf16_t b) { return __uint_as_float(((unsigned)b) << 16); }
; __device__ __forceinline__ unsigned f2bf(float f) { return pk2(f, f) & 0xffffu; }
; __device__ __forceinline__ void mix_c_phase(Frame& F, int l, int rep) {
;     ...
;             const int row0 = MP + 64 * (q - NQ_P);
;             for (int r = 32 * hh; r < 32 * hh + 32; ++r) {
;                 const int s = 8 * (q - NQ_P) + (r >> 3); const size_t row = row0 + r;
;                 const float carry = F.in[I_SH][((size_t)l * NB_S + s) * DB + c];
;                 const float y = (bf2f(YAB[row * D + 512 + c]) + bf2f(PCG[row * 512 + c]) * carry) * bf2f(GGp[row * 512 + c]);
;                 if (rep) ((bf16_t*)(F.ws + WS_U))[row * 512 + c] = (bf16_t)f2bf(y); else
;                 YAB[row * D + 512 + c] = (bf16_t)f2bf(y);
;                 if ((r & 7) == 7) { const f32x2 ph = LAST[(size_t)s * 512 + c]; F.out[O_HS + ((size_t)l * NB_S + s) * DB + c] = ph.y + ph.x * carry; }
;             }
.LBB0_36:
	s_mov_b64 s[26:27], s[2:3]
	v_lshlrev_b32_e32 v7, 1, v170
	v_lshlrev_b32_e32 v56, 2, v170
	v_lshlrev_b32_e32 v57, 3, v170
.Lmixc_sb:
	s_lshr_b32 s2, s8, 3
	s_add_i32 s88, s2, s9
	s_add_i32 s28, s7, s8
	s_lshl_b32 s29, s88, 9
	s_add_i32 s29, s29, s76
	s_lshl_b32 s29, s29, 2
	s_add_u32 s30, s26, s29
	s_addc_u32 s31, s27, 0
	s_add_u32 s36, s72, s29
	s_addc_u32 s37, s73, 0
	s_add_u32 s36, s36, 0x5590000
	s_addc_u32 s37, s37, 0
	s_lshl_b32 s29, s88, 12
	s_add_u32 s34, s74, s29
	s_addc_u32 s35, s75, 0
	s_add_u32 s34, s34, 0x1a0800
	s_addc_u32 s35, s35, 0
	s_lshl_b32 s38, s28, 11
	s_add_u32 s10, s74, s38
	s_addc_u32 s11, s75, 0
	s_add_u32 s10, s10, 0xc641400
	s_addc_u32 s11, s11, 0
	s_add_u32 s12, s10, 0x2000
	s_addc_u32 s13, s11, 0
	s_add_u32 s14, s12, 0x2000
	s_addc_u32 s15, s13, 0
	s_add_u32 s16, s14, 0x2000
	s_addc_u32 s17, s15, 0
	s_lshl_b32 s38, s28, 10
	s_add_u32 s18, s78, s38
	s_addc_u32 s19, s79, 0
	s_add_u32 s18, s18, 0x1000
	s_addc_u32 s19, s19, 0
	s_add_u32 s20, s18, 0x2000
	s_addc_u32 s21, s19, 0
	s_add_u32 s22, s80, s38
	s_addc_u32 s23, s81, 0
	s_add_u32 s22, s22, 0x1000
	s_addc_u32 s23, s23, 0
	s_add_u32 s24, s22, 0x2000
	s_addc_u32 s25, s23, 0
	global_load_dword v58, v56, s[30:31]
	global_load_dword v59, v56, s[30:31] offset:2048
	global_load_dwordx2 v[60:61], v57, s[34:35] offset:-2048
	global_load_dwordx2 v[62:63], v57, s[34:35] offset:2048
	global_load_ushort v8, v7, s[10:11] offset:-4096
	global_load_ushort v24, v7, s[18:19] offset:-4096
	global_load_ushort v40, v7, s[22:23] offset:-4096
	global_load_ushort v9, v7, s[10:11] offset:-2048
	global_load_ushort v25, v7, s[18:19] offset:-3072
	global_load_ushort v41, v7, s[22:23] offset:-3072
	global_load_ushort v10, v7, s[10:11]
	global_load_ushort v26, v7, s[18:19] offset:-2048
	global_load_ushort v42, v7, s[22:23] offset:-2048
	global_load_ushort v11, v7, s[10:11] offset:2048
	global_load_ushort v27, v7, s[18:19] offset:-1024
	global_load_ushort v43, v7, s[22:23] offset:-1024
	global_load_ushort v12, v7, s[12:13] offset:-4096
	global_load_ushort v28, v7, s[18:19]
	global_load_ushort v44, v7, s[22:23]
	global_load_ushort v13, v7, s[12:13] offset:-2048
	global_load_ushort v29, v7, s[18:19] offset:1024
	global_load_ushort v45, v7, s[22:23] offset:1024
	global_load_ushort v14, v7, s[12:13]
	global_load_ushort v30, v7, s[18:19] offset:2048
	global_load_ushort v46, v7, s[22:23] offset:2048
	global_load_ushort v15, v7, s[12:13] offset:2048
	global_load_ushort v31, v7, s[18:19] offset:3072
	global_load_ushort v47, v7, s[22:23] offset:3072
	global_load_ushort v16, v7, s[14:15] offset:-4096
	global_load_ushort v32, v7, s[20:21] offset:-4096
	global_load_ushort v48, v7, s[24:25] offset:-4096
	global_load_ushort v17, v7, s[14:15] offset:-2048
	global_load_ushort v33, v7, s[20:21] offset:-3072
	global_load_ushort v49, v7, s[24:25] offset:-3072
	global_load_ushort v18, v7, s[14:15]
	global_load_ushort v34, v7, s[20:21] offset:-2048
	global_load_ushort v50, v7, s[24:25] offset:-2048
	global_load_ushort v19, v7, s[14:15] offset:2048
	global_load_ushort v35, v7, s[20:21] offset:-1024
	global_load_ushort v51, v7, s[24:25] offset:-1024
	global_load_ushort v20, v7, s[16:17] offset:-4096
	global_load_ushort v36, v7, s[20:21]
	global_load_ushort v52, v7, s[24:25]
	global_load_ushort v21, v7, s[16:17] offset:-2048
	global_load_ushort v37, v7, s[20:21] offset:1024
	global_load_ushort v53, v7, s[24:25] offset:1024
	global_load_ushort v22, v7, s[16:17]
	global_load_ushort v38, v7, s[20:21] offset:2048
	global_load_ushort v54, v7, s[24:25] offset:2048
	global_load_ushort v23, v7, s[16:17] offset:2048
	global_load_ushort v39, v7, s[20:21] offset:3072
	global_load_ushort v55, v7, s[24:25] offset:3072
	s_waitcnt vmcnt(36)
; __device__ __forceinline__ float bf2f(bf16_t b) { return __uint_as_float(((unsigned)b) << 16); }
; __device__ __forceinline__ unsigned f2bf(float f) { return pk2(f, f) & 0xffffu; }
; __device__ __forceinline__ void mix_c_phase(Frame& F, int l, int rep) {
;     ...
;             for (int r = 32 * hh; r < 32 * hh + 32; ++r) {
;                 const int s = 8 * (q - NQ_P) + (r >> 3); const size_t row = row0 + r;
;                 const float carry = F.in[I_SH][((size_t)l * NB_S + s) * DB + c];
;                 const float y = (bf2f(YAB[row * D + 512 + c]) + bf2f(PCG[row * 512 + c]) * carry) * bf2f(GGp[row * 512 + c]);
;                 if (rep) ((bf16_t*)(F.ws + WS_U))[row * 512 + c] = (bf16_t)f2bf(y); else
;                 YAB[row * D + 512 + c] = (bf16_t)f2bf(y);
;                 if ((r & 7) == 7) { const f32x2 ph = LAST[(size_t)s * 512 + c]; F.out[O_HS + ((size_t)l * NB_S + s) * DB + c] = ph.y + ph.x * carry; }
	v_lshlrev_b32_e32 v8, 16, v8
	v_lshlrev_b32_e32 v24, 16, v24
	v_fmac_f32_e32 v8, v58, v24
	v_lshlrev_b32_e32 v40, 16, v40
	v_mul_f32_e32 v8, v8, v40
	v_cvt_pk_bf16_f32 v8, v8, v8
	global_store_short v7, v8, s[10:11] offset:-4096
	v_lshlrev_b32_e32 v9, 16, v9
	v_lshlrev_b32_e32 v25, 16, v25
	v_fmac_f32_e32 v9, v58, v25
	v_lshlrev_b32_e32 v41, 16, v41
	v_mul_f32_e32 v9, v9, v41
	v_cvt_pk_bf16_f32 v9, v9, v9
	global_store_short v7, v9, s[10:11] offset:-2048
	v_lshlrev_b32_e32 v10, 16, v10
	v_lshlrev_b32_e32 v26, 16, v26
	v_fmac_f32_e32 v10, v58, v26
	v_lshlrev_b32_e32 v42, 16, v42
	v_mul_f32_e32 v10, v10, v42
	v_cvt_pk_bf16_f32 v10, v10, v10
	global_store_short v7, v10, s[10:11]
	v_lshlrev_b32_e32 v11, 16, v11
	v_lshlrev_b32_e32 v27, 16, v27
	v_fmac_f32_e32 v11, v58, v27
	v_lshlrev_b32_e32 v43, 16, v43
	v_mul_f32_e32 v11, v11, v43
	v_cvt_pk_bf16_f32 v11, v11, v11
	global_store_short v7, v11, s[10:11] offset:2048
	s_waitcnt vmcnt(28)
	v_lshlrev_b32_e32 v12, 16, v12
	v_lshlrev_b32_e32 v28, 16, v28
	v_fmac_f32_e32 v12, v58, v28
	v_lshlrev_b32_e32 v44, 16, v44
	v_mul_f32_e32 v12, v12, v44
	v_cvt_pk_bf16_f32 v12, v12, v12
	global_store_short v7, v12, s[12:13] offset:-4096
	v_lshlrev_b32_e32 v13, 16, v13
	v_lshlrev_b32_e32 v29, 16, v29
	v_fmac_f32_e32 v13, v58, v29
	v_lshlrev_b32_e32 v45, 16, v45
	v_mul_f32_e32 v13, v13, v45
	v_cvt_pk_bf16_f32 v13, v13, v13
	global_store_short v7, v13, s[12:13] offset:-2048
	v_lshlrev_b32_e32 v14, 16, v14
	v_lshlrev_b32_e32 v30, 16, v30
	v_fmac_f32_e32 v14, v58, v30
	v_lshlrev_b32_e32 v46, 16, v46
	v_mul_f32_e32 v14, v14, v46
	v_cvt_pk_bf16_f32 v14, v14, v14
	global_store_short v7, v14, s[12:13]
	v_lshlrev_b32_e32 v15, 16, v15
	v_lshlrev_b32_e32 v31, 16, v31
	v_fmac_f32_e32 v15, v58, v31
	v_lshlrev_b32_e32 v47, 16, v47
	v_mul_f32_e32 v15, v15, v47
	v_cvt_pk_bf16_f32 v15, v15, v15
	global_store_short v7, v15, s[12:13] offset:2048
	s_waitcnt vmcnt(20)
	v_lshlrev_b32_e32 v16, 16, v16
	v_lshlrev_b32_e32 v32, 16, v32
	v_fmac_f32_e32 v16, v59, v32
	v_lshlrev_b32_e32 v48, 16, v48
	v_mul_f32_e32 v16, v16, v48
	v_cvt_pk_bf16_f32 v16, v16, v16
	global_store_short v7, v16, s[14:15] offset:-4096
	v_lshlrev_b32_e32 v17, 16, v17
	v_lshlrev_b32_e32 v33, 16, v33
	v_fmac_f32_e32 v17, v59, v33
	v_lshlrev_b32_e32 v49, 16, v49
	v_mul_f32_e32 v17, v17, v49
	v_cvt_pk_bf16_f32 v17, v17, v17
	global_store_short v7, v17, s[14:15] offset:-2048
	v_lshlrev_b32_e32 v18, 16, v18
	v_lshlrev_b32_e32 v34, 16, v34
	v_fmac_f32_e32 v18, v59, v34
	v_lshlrev_b32_e32 v50, 16, v50
	v_mul_f32_e32 v18, v18, v50
	v_cvt_pk_bf16_f32 v18, v18, v18
	global_store_short v7, v18, s[14:15]
	v_lshlrev_b32_e32 v19, 16, v19
	v_lshlrev_b32_e32 v35, 16, v35
	v_fmac_f32_e32 v19, v59, v35
	v_lshlrev_b32_e32 v51, 16, v51
	v_mul_f32_e32 v19, v19, v51
	v_cvt_pk_bf16_f32 v19, v19, v19
	global_store_short v7, v19, s[14:15] offset:2048
	s_waitcnt vmcnt(12)
	v_lshlrev_b32_e32 v20, 16, v20
	v_lshlrev_b32_e32 v36, 16, v36
	v_fmac_f32_e32 v20, v59, v36
	v_lshlrev_b32_e32 v52, 16, v52
	v_mul_f32_e32 v20, v20, v52
	v_cvt_pk_bf16_f32 v20, v20, v20
	global_store_short v7, v20, s[16:17] offset:-4096
	v_lshlrev_b32_e32 v21, 16, v21
	v_lshlrev_b32_e32 v37, 16, v37
	v_fmac_f32_e32 v21, v59, v37
	v_lshlrev_b32_e32 v53, 16, v53
	v_mul_f32_e32 v21, v21, v53
	v_cvt_pk_bf16_f32 v21, v21, v21
	global_store_short v7, v21, s[16:17] offset:-2048
	v_lshlrev_b32_e32 v22, 16, v22
	v_lshlrev_b32_e32 v38, 16, v38
	v_fmac_f32_e32 v22, v59, v38
	v_lshlrev_b32_e32 v54, 16, v54
	v_mul_f32_e32 v22, v22, v54
	v_cvt_pk_bf16_f32 v22, v22, v22
	global_store_short v7, v22, s[16:17]
	v_lshlrev_b32_e32 v23, 16, v23
	v_lshlrev_b32_e32 v39, 16, v39
	v_fmac_f32_e32 v23, v59, v39
	v_lshlrev_b32_e32 v55, 16, v55
	v_mul_f32_e32 v23, v23, v55
	v_cvt_pk_bf16_f32 v23, v23, v23
	global_store_short v7, v23, s[16:17] offset:2048
	v_fmac_f32_e32 v61, v58, v60
	v_fmac_f32_e32 v63, v59, v62
	global_store_dword v56, v61, s[36:37]
	global_store_dword v56, v63, s[36:37] offset:2048
	s_add_i32 s8, s8, 16
	s_cmp_lg_u32 s6, s8
	s_cbranch_scc1 .Lmixc_sb

; __device__ __forceinline__ float bf2f(bf16_t b) { return __uint_as_float(((unsigned)b) << 16); }
; __device__ __forceinline__ unsigned f2bf(float f) { return pk2(f, f) & 0xffffu; }
; __device__ __forceinline__ void mix_c_phase(Frame& F, int l, int rep) {
;     ...
;             const int r1 = (32 * hh + 32 < nvalid) ? 32 * hh + 32 : nvalid;
;             for (int r = 32 * hh; r < r1; ++r) {
;                 const size_t row = row0 + r;
;                 const float y = (bf2f(YAB[row * D + 512 + c]) + bf2f(PCG[row * 512 + c]) * carry) * bf2f(GGp[row * 512 + c]);
;                 if (rep) ((bf16_t*)(F.ws + WS_U))[row * 512 + c] = (bf16_t)f2bf(y); else
;                 YAB[row * D + 512 + c] = (bf16_t)f2bf(y);
;             }
.LBB0_42:
	v_lshlrev_b32_e32 v7, 1, v170
.Lmixc_pb:
	s_add_i32 s8, s88, s3
	s_lshl_b32 s38, s8, 11
	s_add_u32 s10, s74, s38
	s_addc_u32 s11, s75, 0
	s_add_u32 s10, s10, 0xc641400
	s_addc_u32 s11, s11, 0
	s_add_u32 s12, s10, 0x2000
	s_addc_u32 s13, s11, 0
	s_add_u32 s14, s12, 0x2000
	s_addc_u32 s15, s13, 0
	s_add_u32 s16, s14, 0x2000
	s_addc_u32 s17, s15, 0
	s_lshl_b32 s38, s8, 10
	s_add_u32 s18, s78, s38
	s_addc_u32 s19, s79, 0
	s_add_u32 s18, s18, 0x1000
	s_addc_u32 s19, s19, 0
	s_add_u32 s20, s18, 0x2000
	s_addc_u32 s21, s19, 0
	s_add_u32 s22, s80, s38
	s_addc_u32 s23, s81, 0
	s_add_u32 s22, s22, 0x1000
	s_addc_u32 s23, s23, 0
	s_add_u32 s24, s22, 0x2000
	s_addc_u32 s25, s23, 0
	global_load_ushort v8, v7, s[10:11] offset:-4096
	global_load_ushort v24, v7, s[18:19] offset:-4096
	global_load_ushort v40, v7, s[22:23] offset:-4096
	global_load_ushort v9, v7, s[10:11] offset:-2048
	global_load_ushort v25, v7, s[18:19] offset:-3072
	global_load_ushort v41, v7, s[22:23] offset:-3072
	global_load_ushort v10, v7, s[10:11]
	global_load_ushort v26, v7, s[18:19] offset:-2048
	global_load_ushort v42, v7, s[22:23] offset:-2048
	global_load_ushort v11, v7, s[10:11] offset:2048
	global_load_ushort v27, v7, s[18:19] offset:-1024
	global_load_ushort v43, v7, s[22:23] offset:-1024
	global_load_ushort v12, v7, s[12:13] offset:-4096
	global_load_ushort v28, v7, s[18:19]
	global_load_ushort v44, v7, s[22:23]
	global_load_ushort v13, v7, s[12:13] offset:-2048
	global_load_ushort v29, v7, s[18:19] offset:1024
	global_load_ushort v45, v7, s[22:23] offset:1024
	global_load_ushort v14, v7, s[12:13]
	global_load_ushort v30, v7, s[18:19] offset:2048
	global_load_ushort v46, v7, s[22:23] offset:2048
	global_load_ushort v15, v7, s[12:13] offset:2048
	global_load_ushort v31, v7, s[18:19] offset:3072
	global_load_ushort v47, v7, s[22:23] offset:3072
	global_load_ushort v16, v7, s[14:15] offset:-4096
	global_load_ushort v32, v7, s[20:21] offset:-4096
	global_load_ushort v48, v7, s[24:25] offset:-4096
	global_load_ushort v17, v7, s[14:15] offset:-2048
	global_load_ushort v33, v7, s[20:21] offset:-3072
	global_load_ushort v49, v7, s[24:25] offset:-3072
	global_load_ushort v18, v7, s[14:15]
	global_load_ushort v34, v7, s[20:21] offset:-2048
	global_load_ushort v50, v7, s[24:25] offset:-2048
	global_load_ushort v19, v7, s[14:15] offset:2048
	global_load_ushort v35, v7, s[20:21] offset:-1024
	global_load_ushort v51, v7, s[24:25] offset:-1024
	global_load_ushort v20, v7, s[16:17] offset:-4096
	global_load_ushort v36, v7, s[20:21]
	global_load_ushort v52, v7, s[24:25]
	global_load_ushort v21, v7, s[16:17] offset:-2048
	global_load_ushort v37, v7, s[20:21] offset:1024
	global_load_ushort v53, v7, s[24:25] offset:1024
	global_load_ushort v22, v7, s[16:17]
	global_load_ushort v38, v7, s[20:21] offset:2048
	global_load_ushort v54, v7, s[24:25] offset:2048
	global_load_ushort v23, v7, s[16:17] offset:2048
	global_load_ushort v39, v7, s[20:21] offset:3072
	global_load_ushort v55, v7, s[24:25] offset:3072
	s_waitcnt vmcnt(36)
	v_lshlrev_b32_e32 v8, 16, v8
	v_lshlrev_b32_e32 v24, 16, v24
	v_fmac_f32_e32 v8, v6, v24
	v_lshlrev_b32_e32 v40, 16, v40
	v_mul_f32_e32 v8, v8, v40
	v_cvt_pk_bf16_f32 v8, v8, v8
	global_store_short v7, v8, s[10:11] offset:-4096
	v_lshlrev_b32_e32 v9, 16, v9
	v_lshlrev_b32_e32 v25, 16, v25
	v_fmac_f32_e32 v9, v6, v25
	v_lshlrev_b32_e32 v41, 16, v41
	v_mul_f32_e32 v9, v9, v41
	v_cvt_pk_bf16_f32 v9, v9, v9
	global_store_short v7, v9, s[10:11] offset:-2048
	v_lshlrev_b32_e32 v10, 16, v10
	v_lshlrev_b32_e32 v26, 16, v26
	v_fmac_f32_e32 v10, v6, v26
	v_lshlrev_b32_e32 v42, 16, v42
	v_mul_f32_e32 v10, v10, v42
	v_cvt_pk_bf16_f32 v10, v10, v10
	global_store_short v7, v10, s[10:11]
	v_lshlrev_b32_e32 v11, 16, v11
	v_lshlrev_b32_e32 v27, 16, v27
	v_fmac_f32_e32 v11, v6, v27
	v_lshlrev_b32_e32 v43, 16, v43
	v_mul_f32_e32 v11, v11, v43
	v_cvt_pk_bf16_f32 v11, v11, v11
	global_store_short v7, v11, s[10:11] offset:2048
	s_waitcnt vmcnt(28)
	v_lshlrev_b32_e32 v12, 16, v12
	v_lshlrev_b32_e32 v28, 16, v28
	v_fmac_f32_e32 v12, v6, v28
	v_lshlrev_b32_e32 v44, 16, v44
	v_mul_f32_e32 v12, v12, v44
	v_cvt_pk_bf16_f32 v12, v12, v12
	global_store_short v7, v12, s[12:13] offset:-4096
	v_lshlrev_b32_e32 v13, 16, v13
	v_lshlrev_b32_e32 v29, 16, v29
	v_fmac_f32_e32 v13, v6, v29
	v_lshlrev_b32_e32 v45, 16, v45
	v_mul_f32_e32 v13, v13, v45
	v_cvt_pk_bf16_f32 v13, v13, v13
	global_store_short v7, v13, s[12:13] offset:-2048
	v_lshlrev_b32_e32 v14, 16, v14
	v_lshlrev_b32_e32 v30, 16, v30
	v_fmac_f32_e32 v14, v6, v30
	v_lshlrev_b32_e32 v46, 16, v46
	v_mul_f32_e32 v14, v14, v46
	v_cvt_pk_bf16_f32 v14, v14, v14
	global_store_short v7, v14, s[12:13]
	v_lshlrev_b32_e32 v15, 16, v15
	v_lshlrev_b32_e32 v31, 16, v31
	v_fmac_f32_e32 v15, v6, v31
	v_lshlrev_b32_e32 v47, 16, v47
	v_mul_f32_e32 v15, v15, v47
	v_cvt_pk_bf16_f32 v15, v15, v15
	global_store_short v7, v15, s[12:13] offset:2048
	s_waitcnt vmcnt(20)
	v_lshlrev_b32_e32 v16, 16, v16
	v_lshlrev_b32_e32 v32, 16, v32
	v_fmac_f32_e32 v16, v6, v32
	v_lshlrev_b32_e32 v48, 16, v48
	v_mul_f32_e32 v16, v16, v48
	v_cvt_pk_bf16_f32 v16, v16, v16
	global_store_short v7, v16, s[14:15] offset:-4096
	v_lshlrev_b32_e32 v17, 16, v17
	v_lshlrev_b32_e32 v33, 16, v33
	v_fmac_f32_e32 v17, v6, v33
	v_lshlrev_b32_e32 v49, 16, v49
	v_mul_f32_e32 v17, v17, v49
	v_cvt_pk_bf16_f32 v17, v17, v17
	global_store_short v7, v17, s[14:15] offset:-2048
	v_lshlrev_b32_e32 v18, 16, v18
	v_lshlrev_b32_e32 v34, 16, v34
	v_fmac_f32_e32 v18, v6, v34
	v_lshlrev_b32_e32 v50, 16, v50
	v_mul_f32_e32 v18, v18, v50
	v_cvt_pk_bf16_f32 v18, v18, v18
	global_store_short v7, v18, s[14:15]
	v_lshlrev_b32_e32 v19, 16, v19
	v_lshlrev_b32_e32 v35, 16, v35
	v_fmac_f32_e32 v19, v6, v35
	v_lshlrev_b32_e32 v51, 16, v51
	v_mul_f32_e32 v19, v19, v51
	v_cvt_pk_bf16_f32 v19, v19, v19
	global_store_short v7, v19, s[14:15] offset:2048
	s_waitcnt vmcnt(12)
	v_lshlrev_b32_e32 v20, 16, v20
	v_lshlrev_b32_e32 v36, 16, v36
	v_fmac_f32_e32 v20, v6, v36
	v_lshlrev_b32_e32 v52, 16, v52
	v_mul_f32_e32 v20, v20, v52
	v_cvt_pk_bf16_f32 v20, v20, v20
	global_store_short v7, v20, s[16:17] offset:-4096
	v_lshlrev_b32_e32 v21, 16, v21
	v_lshlrev_b32_e32 v37, 16, v37
	v_fmac_f32_e32 v21, v6, v37
	v_lshlrev_b32_e32 v53, 16, v53
	v_mul_f32_e32 v21, v21, v53
	v_cvt_pk_bf16_f32 v21, v21, v21
	global_store_short v7, v21, s[16:17] offset:-2048
	v_lshlrev_b32_e32 v22, 16, v22
	v_lshlrev_b32_e32 v38, 16, v38
	v_fmac_f32_e32 v22, v6, v38
	v_lshlrev_b32_e32 v54, 16, v54
	v_mul_f32_e32 v22, v22, v54
	v_cvt_pk_bf16_f32 v22, v22, v22
	global_store_short v7, v22, s[16:17]
	v_lshlrev_b32_e32 v23, 16, v23
	v_lshlrev_b32_e32 v39, 16, v39
	v_fmac_f32_e32 v23, v6, v39
	v_lshlrev_b32_e32 v55, 16, v55
	v_mul_f32_e32 v23, v23, v55
	v_cvt_pk_bf16_f32 v23, v23, v23
	global_store_short v7, v23, s[16:17] offset:2048
	s_add_i32 s3, s3, 16
	s_cmp_ge_u32 s3, s6
	s_cbranch_scc0 .Lmixc_pb
; __device__ __forceinline__ void mix_c_phase(Frame& F, int l, int rep) {
;     ...
;             if (k == NCH_P - 1 && hh == 0) { const f32x2 ph = SUMM[(size_t)q * 512 + c]; F.out[O_HP + ((size_t)l * NB_P + b) * DB + c] = ph.y + ph.x * carry; }
	s_cmp_eq_u32 s87, 0
	s_cselect_b64 s[6:7], -1, 0
	s_and_b64 s[6:7], s[6:7], s[70:71]
	s_and_b64 vcc, exec, s[6:7]
	s_cbranch_vccz .LBB0_31
	s_ashr_i32 s87, s86, 31
	s_lshl_b64 s[6:7], s[86:87], 12
	v_lshl_add_u64 v[8:9], v[2:3], 0, s[6:7]
	global_load_dwordx2 v[8:9], v[8:9], off
	s_ashr_i32 s3, s2, 31
	s_lshl_b64 s[2:3], s[2:3], 11
	v_readlane_b32 s6, v255, 18
	s_add_u32 s2, s6, s2
	v_readlane_b32 s6, v255, 19
	s_addc_u32 s3, s6, s3
	s_waitcnt vmcnt(0)
	v_fmac_f32_e32 v9, v6, v8
	v_lshl_add_u64 v[6:7], v[170:171], 2, s[2:3]
	v_add_co_u32_e32 v6, vcc, 0x4508000, v6
	s_nop 1
	v_addc_co_u32_e32 v7, vcc, 0, v7, vcc
	global_store_dword v[6:7], v9, off
	s_branch .LBB0_31
